# FFN1 epilogue rewritten: 8 elements interleaved (no dependent-chain stalls), 32-bit offset + SGPR-base stores instead of per-element 64-bit mad
# speedup vs baseline: 1.0111x; 1.0111x over previous
; DI int TIDX() { int t = threadIdx.x; asm volatile("" : "+v"(t)); return t; }
; DI float sigmoidf_(float x) { return __builtin_amdgcn_rcpf(1.f + __expf(-x)); }
; DI void phase_ffn1(const P& p, int l, int hf, char* smem) {
;     ...
;     const int lane = TIDX() & 63, w = TIDX() >> 6, wm = w >> 1, wn = w & 1, hh = lane >> 5, c = lane & 31;
;     const int ml0 = m0 - mt0 * 128;
; #pragma unroll
;     for (int mi = 0; mi < 4; ++mi) {
;       const int rbase = ml0 + wm * 128 + mi * 32 + 4 * hh, n = c0 + wn * 32 + c;
; #pragma unroll
;       for (int i = 0; i < 16; ++i) {
;         const float g = acc[mi][0][i];
;         act[(size_t)EROW(rbase, i) * 2816 + n] = (h16)(g * sigmoidf_(g) * acc[mi][1][i]);
;       }
;     }
.LBB0_69:
	v_mov_b32_e32 v0, v203
	v_mov_b32_e32 v130, v203
	s_barrier
	s_movk_i32 s2, 0x1600
	v_and_b32_e32 v132, 0xffffff80, v203
	v_add_u32_e32 v132, s12, v132
	v_lshrrev_b32_e32 v133, 3, v203
	v_and_or_b32 v132, v133, 4, v132
	v_and_b32_e32 v131, 31, v203
	v_lshrrev_b32_e32 v130, 1, v203
	v_and_b32_e32 v130, 32, v130
	v_or3_b32 v130, v131, v130, s26
	v_lshlrev_b32_e32 v130, 1, v130
	v_mad_u32_u24 v130, v132, s2, v130
	v_mul_f32_e32 v178, 0xbfb8aa3b, v114
	v_mul_f32_e32 v179, 0xbfb8aa3b, v115
	v_mul_f32_e32 v180, 0xbfb8aa3b, v116
	v_mul_f32_e32 v181, 0xbfb8aa3b, v117
	v_mul_f32_e32 v182, 0xbfb8aa3b, v118
	v_mul_f32_e32 v183, 0xbfb8aa3b, v119
	v_mul_f32_e32 v184, 0xbfb8aa3b, v120
	v_mul_f32_e32 v185, 0xbfb8aa3b, v121
	v_exp_f32_e32 v178, v178
	v_exp_f32_e32 v179, v179
	v_exp_f32_e32 v180, v180
	v_exp_f32_e32 v181, v181
	v_exp_f32_e32 v182, v182
	v_exp_f32_e32 v183, v183
	v_exp_f32_e32 v184, v184
	v_exp_f32_e32 v185, v185
	v_mov_b32_e32 v186, v130
	v_add_u32_e32 v187, 0x1600, v130
	v_add_u32_e32 v188, 0x2c00, v130
	v_add_u32_e32 v189, 0x4200, v130
	v_add_u32_e32 v190, 0xb000, v130
	v_add_u32_e32 v191, 0xc600, v130
	v_add_u32_e32 v192, 0xdc00, v130
	v_add_u32_e32 v193, 0xf200, v130
	v_add_f32_e32 v178, 1.0, v178
	v_add_f32_e32 v179, 1.0, v179
	v_add_f32_e32 v180, 1.0, v180
	v_add_f32_e32 v181, 1.0, v181
	v_add_f32_e32 v182, 1.0, v182
	v_add_f32_e32 v183, 1.0, v183
	v_add_f32_e32 v184, 1.0, v184
	v_add_f32_e32 v185, 1.0, v185
	v_rcp_f32_e32 v178, v178
	v_rcp_f32_e32 v179, v179
	v_rcp_f32_e32 v180, v180
	v_rcp_f32_e32 v181, v181
	v_rcp_f32_e32 v182, v182
	v_rcp_f32_e32 v183, v183
	v_rcp_f32_e32 v184, v184
	v_rcp_f32_e32 v185, v185
	v_mul_f32_e32 v178, v114, v178
	v_mul_f32_e32 v179, v115, v179
	v_mul_f32_e32 v180, v116, v180
	v_mul_f32_e32 v181, v117, v181
	v_mul_f32_e32 v182, v118, v182
	v_mul_f32_e32 v183, v119, v183
	v_mul_f32_e32 v184, v120, v184
	v_mul_f32_e32 v185, v121, v185
	v_fma_mixlo_f16 v178, v98, v178, 0
	v_fma_mixlo_f16 v179, v99, v179, 0
	v_fma_mixlo_f16 v180, v100, v180, 0
	v_fma_mixlo_f16 v181, v101, v181, 0
	v_fma_mixlo_f16 v182, v102, v182, 0
	v_fma_mixlo_f16 v183, v103, v183, 0
	v_fma_mixlo_f16 v184, v104, v184, 0
	v_fma_mixlo_f16 v185, v105, v185, 0
	global_store_short v186, v178, s[8:9]
	global_store_short v187, v179, s[8:9]
	global_store_short v188, v180, s[8:9]
	global_store_short v189, v181, s[8:9]
	global_store_short v190, v182, s[8:9]
	global_store_short v191, v183, s[8:9]
	global_store_short v192, v184, s[8:9]
	global_store_short v193, v185, s[8:9]
	v_mul_f32_e32 v178, 0xbfb8aa3b, v122
	v_mul_f32_e32 v179, 0xbfb8aa3b, v123
	v_mul_f32_e32 v180, 0xbfb8aa3b, v124
	v_mul_f32_e32 v181, 0xbfb8aa3b, v125
	v_mul_f32_e32 v182, 0xbfb8aa3b, v126
	v_mul_f32_e32 v183, 0xbfb8aa3b, v127
	v_mul_f32_e32 v184, 0xbfb8aa3b, v128
	v_mul_f32_e32 v185, 0xbfb8aa3b, v129
	v_exp_f32_e32 v178, v178
	v_exp_f32_e32 v179, v179
	v_exp_f32_e32 v180, v180
	v_exp_f32_e32 v181, v181
	v_exp_f32_e32 v182, v182
	v_exp_f32_e32 v183, v183
	v_exp_f32_e32 v184, v184
	v_exp_f32_e32 v185, v185
	v_add_u32_e32 v186, 0x16000, v130
	v_add_u32_e32 v187, 0x17600, v130
	v_add_u32_e32 v188, 0x18c00, v130
	v_add_u32_e32 v189, 0x1a200, v130
	v_add_u32_e32 v190, 0x21000, v130
	v_add_u32_e32 v191, 0x22600, v130
	v_add_u32_e32 v192, 0x23c00, v130
	v_add_u32_e32 v193, 0x25200, v130
	v_add_f32_e32 v178, 1.0, v178
	v_add_f32_e32 v179, 1.0, v179
	v_add_f32_e32 v180, 1.0, v180
	v_add_f32_e32 v181, 1.0, v181
	v_add_f32_e32 v182, 1.0, v182
	v_add_f32_e32 v183, 1.0, v183
	v_add_f32_e32 v184, 1.0, v184
	v_add_f32_e32 v185, 1.0, v185
	v_rcp_f32_e32 v178, v178
	v_rcp_f32_e32 v179, v179
	v_rcp_f32_e32 v180, v180
	v_rcp_f32_e32 v181, v181
	v_rcp_f32_e32 v182, v182
	v_rcp_f32_e32 v183, v183
	v_rcp_f32_e32 v184, v184
	v_rcp_f32_e32 v185, v185
	v_mul_f32_e32 v178, v122, v178
	v_mul_f32_e32 v179, v123, v179
	v_mul_f32_e32 v180, v124, v180
	v_mul_f32_e32 v181, v125, v181
	v_mul_f32_e32 v182, v126, v182
	v_mul_f32_e32 v183, v127, v183
	v_mul_f32_e32 v184, v128, v184
	v_mul_f32_e32 v185, v129, v185
	v_fma_mixlo_f16 v178, v106, v178, 0
	v_fma_mixlo_f16 v179, v107, v179, 0
	v_fma_mixlo_f16 v180, v108, v180, 0
	v_fma_mixlo_f16 v181, v109, v181, 0
	v_fma_mixlo_f16 v182, v110, v182, 0
	v_fma_mixlo_f16 v183, v111, v183, 0
	v_fma_mixlo_f16 v184, v112, v184, 0
	v_fma_mixlo_f16 v185, v113, v185, 0
	global_store_short v186, v178, s[8:9]
	global_store_short v187, v179, s[8:9]
	global_store_short v188, v180, s[8:9]
	global_store_short v189, v181, s[8:9]
	global_store_short v190, v182, s[8:9]
	global_store_short v191, v183, s[8:9]
	global_store_short v192, v184, s[8:9]
	global_store_short v193, v185, s[8:9]
	v_mul_f32_e32 v178, 0xbfb8aa3b, v82
	v_mul_f32_e32 v179, 0xbfb8aa3b, v83
	v_mul_f32_e32 v180, 0xbfb8aa3b, v84
	v_mul_f32_e32 v181, 0xbfb8aa3b, v85
	v_mul_f32_e32 v182, 0xbfb8aa3b, v86
	v_mul_f32_e32 v183, 0xbfb8aa3b, v87
	v_mul_f32_e32 v184, 0xbfb8aa3b, v88
	v_mul_f32_e32 v185, 0xbfb8aa3b, v89
	v_exp_f32_e32 v178, v178
	v_exp_f32_e32 v179, v179
	v_exp_f32_e32 v180, v180
	v_exp_f32_e32 v181, v181
	v_exp_f32_e32 v182, v182
	v_exp_f32_e32 v183, v183
	v_exp_f32_e32 v184, v184
	v_exp_f32_e32 v185, v185
	v_add_u32_e32 v186, 0x2c000, v130
	v_add_u32_e32 v187, 0x2d600, v130
	v_add_u32_e32 v188, 0x2ec00, v130
	v_add_u32_e32 v189, 0x30200, v130
	v_add_u32_e32 v190, 0x37000, v130
	v_add_u32_e32 v191, 0x38600, v130
	v_add_u32_e32 v192, 0x39c00, v130
	v_add_u32_e32 v193, 0x3b200, v130
	v_add_f32_e32 v178, 1.0, v178
	v_add_f32_e32 v179, 1.0, v179
	v_add_f32_e32 v180, 1.0, v180
	v_add_f32_e32 v181, 1.0, v181
	v_add_f32_e32 v182, 1.0, v182
	v_add_f32_e32 v183, 1.0, v183
	v_add_f32_e32 v184, 1.0, v184
; DI int TIDX() { int t = threadIdx.x; asm volatile("" : "+v"(t)); return t; }
; DI float sigmoidf_(float x) { return __builtin_amdgcn_rcpf(1.f + __expf(-x)); }
; DI void phase_ffn1(const P& p, int l, int hf, char* smem) {
;     ...
;     const int lane = TIDX() & 63, w = TIDX() >> 6, wm = w >> 1, wn = w & 1, hh = lane >> 5, c = lane & 31;
;     const int ml0 = m0 - mt0 * 128;
; #pragma unroll
;     for (int mi = 0; mi < 4; ++mi) {
;       const int rbase = ml0 + wm * 128 + mi * 32 + 4 * hh, n = c0 + wn * 32 + c;
; #pragma unroll
;       for (int i = 0; i < 16; ++i) {
;         const float g = acc[mi][0][i];
;         act[(size_t)EROW(rbase, i) * 2816 + n] = (h16)(g * sigmoidf_(g) * acc[mi][1][i]);
;       }
;     }
	v_add_f32_e32 v185, 1.0, v185
	v_rcp_f32_e32 v178, v178
	v_rcp_f32_e32 v179, v179
	v_rcp_f32_e32 v180, v180
	v_rcp_f32_e32 v181, v181
	v_rcp_f32_e32 v182, v182
	v_rcp_f32_e32 v183, v183
	v_rcp_f32_e32 v184, v184
	v_rcp_f32_e32 v185, v185
	v_mul_f32_e32 v178, v82, v178
	v_mul_f32_e32 v179, v83, v179
	v_mul_f32_e32 v180, v84, v180
	v_mul_f32_e32 v181, v85, v181
	v_mul_f32_e32 v182, v86, v182
	v_mul_f32_e32 v183, v87, v183
	v_mul_f32_e32 v184, v88, v184
	v_mul_f32_e32 v185, v89, v185
	v_fma_mixlo_f16 v178, v66, v178, 0
	v_fma_mixlo_f16 v179, v67, v179, 0
	v_fma_mixlo_f16 v180, v68, v180, 0
	v_fma_mixlo_f16 v181, v69, v181, 0
	v_fma_mixlo_f16 v182, v70, v182, 0
	v_fma_mixlo_f16 v183, v71, v183, 0
	v_fma_mixlo_f16 v184, v72, v184, 0
	v_fma_mixlo_f16 v185, v73, v185, 0
	global_store_short v186, v178, s[8:9]
	global_store_short v187, v179, s[8:9]
	global_store_short v188, v180, s[8:9]
	global_store_short v189, v181, s[8:9]
	global_store_short v190, v182, s[8:9]
	global_store_short v191, v183, s[8:9]
	global_store_short v192, v184, s[8:9]
	global_store_short v193, v185, s[8:9]
	v_mul_f32_e32 v178, 0xbfb8aa3b, v90
	v_mul_f32_e32 v179, 0xbfb8aa3b, v91
	v_mul_f32_e32 v180, 0xbfb8aa3b, v92
	v_mul_f32_e32 v181, 0xbfb8aa3b, v93
	v_mul_f32_e32 v182, 0xbfb8aa3b, v94
	v_mul_f32_e32 v183, 0xbfb8aa3b, v95
	v_mul_f32_e32 v184, 0xbfb8aa3b, v96
	v_mul_f32_e32 v185, 0xbfb8aa3b, v97
	v_exp_f32_e32 v178, v178
	v_exp_f32_e32 v179, v179
	v_exp_f32_e32 v180, v180
	v_exp_f32_e32 v181, v181
	v_exp_f32_e32 v182, v182
	v_exp_f32_e32 v183, v183
	v_exp_f32_e32 v184, v184
	v_exp_f32_e32 v185, v185
	v_add_u32_e32 v186, 0x42000, v130
	v_add_u32_e32 v187, 0x43600, v130
	v_add_u32_e32 v188, 0x44c00, v130
	v_add_u32_e32 v189, 0x46200, v130
	v_add_u32_e32 v190, 0x4d000, v130
	v_add_u32_e32 v191, 0x4e600, v130
	v_add_u32_e32 v192, 0x4fc00, v130
	v_add_u32_e32 v193, 0x51200, v130
	v_add_f32_e32 v178, 1.0, v178
	v_add_f32_e32 v179, 1.0, v179
	v_add_f32_e32 v180, 1.0, v180
	v_add_f32_e32 v181, 1.0, v181
	v_add_f32_e32 v182, 1.0, v182
	v_add_f32_e32 v183, 1.0, v183
	v_add_f32_e32 v184, 1.0, v184
	v_add_f32_e32 v185, 1.0, v185
	v_rcp_f32_e32 v178, v178
	v_rcp_f32_e32 v179, v179
	v_rcp_f32_e32 v180, v180
	v_rcp_f32_e32 v181, v181
	v_rcp_f32_e32 v182, v182
	v_rcp_f32_e32 v183, v183
	v_rcp_f32_e32 v184, v184
	v_rcp_f32_e32 v185, v185
	v_mul_f32_e32 v178, v90, v178
	v_mul_f32_e32 v179, v91, v179
	v_mul_f32_e32 v180, v92, v180
	v_mul_f32_e32 v181, v93, v181
	v_mul_f32_e32 v182, v94, v182
	v_mul_f32_e32 v183, v95, v183
	v_mul_f32_e32 v184, v96, v184
	v_mul_f32_e32 v185, v97, v185
	v_fma_mixlo_f16 v178, v74, v178, 0
	v_fma_mixlo_f16 v179, v75, v179, 0
	v_fma_mixlo_f16 v180, v76, v180, 0
	v_fma_mixlo_f16 v181, v77, v181, 0
	v_fma_mixlo_f16 v182, v78, v182, 0
	v_fma_mixlo_f16 v183, v79, v183, 0
	v_fma_mixlo_f16 v184, v80, v184, 0
	v_fma_mixlo_f16 v185, v81, v185, 0
	global_store_short v186, v178, s[8:9]
	global_store_short v187, v179, s[8:9]
	global_store_short v188, v180, s[8:9]
	global_store_short v189, v181, s[8:9]
	global_store_short v190, v182, s[8:9]
	global_store_short v191, v183, s[8:9]
	global_store_short v192, v184, s[8:9]
	global_store_short v193, v185, s[8:9]
	v_mul_f32_e32 v178, 0xbfb8aa3b, v50
	v_mul_f32_e32 v179, 0xbfb8aa3b, v51
	v_mul_f32_e32 v180, 0xbfb8aa3b, v52
	v_mul_f32_e32 v181, 0xbfb8aa3b, v53
	v_mul_f32_e32 v182, 0xbfb8aa3b, v54
	v_mul_f32_e32 v183, 0xbfb8aa3b, v55
	v_mul_f32_e32 v184, 0xbfb8aa3b, v56
	v_mul_f32_e32 v185, 0xbfb8aa3b, v57
	v_exp_f32_e32 v178, v178
	v_exp_f32_e32 v179, v179
	v_exp_f32_e32 v180, v180
	v_exp_f32_e32 v181, v181
	v_exp_f32_e32 v182, v182
	v_exp_f32_e32 v183, v183
	v_exp_f32_e32 v184, v184
	v_exp_f32_e32 v185, v185
	v_add_u32_e32 v186, 0x58000, v130
	v_add_u32_e32 v187, 0x59600, v130
	v_add_u32_e32 v188, 0x5ac00, v130
	v_add_u32_e32 v189, 0x5c200, v130
	v_add_u32_e32 v190, 0x63000, v130
	v_add_u32_e32 v191, 0x64600, v130
	v_add_u32_e32 v192, 0x65c00, v130
	v_add_u32_e32 v193, 0x67200, v130
	v_add_f32_e32 v178, 1.0, v178
	v_add_f32_e32 v179, 1.0, v179
	v_add_f32_e32 v180, 1.0, v180
	v_add_f32_e32 v181, 1.0, v181
	v_add_f32_e32 v182, 1.0, v182
	v_add_f32_e32 v183, 1.0, v183
	v_add_f32_e32 v184, 1.0, v184
	v_add_f32_e32 v185, 1.0, v185
	v_rcp_f32_e32 v178, v178
	v_rcp_f32_e32 v179, v179
	v_rcp_f32_e32 v180, v180
	v_rcp_f32_e32 v181, v181
	v_rcp_f32_e32 v182, v182
	v_rcp_f32_e32 v183, v183
	v_rcp_f32_e32 v184, v184
	v_rcp_f32_e32 v185, v185
	v_mul_f32_e32 v178, v50, v178
	v_mul_f32_e32 v179, v51, v179
	v_mul_f32_e32 v180, v52, v180
	v_mul_f32_e32 v181, v53, v181
	v_mul_f32_e32 v182, v54, v182
	v_mul_f32_e32 v183, v55, v183
	v_mul_f32_e32 v184, v56, v184
	v_mul_f32_e32 v185, v57, v185
	v_fma_mixlo_f16 v178, v34, v178, 0
	v_fma_mixlo_f16 v179, v35, v179, 0
	v_fma_mixlo_f16 v180, v36, v180, 0
	v_fma_mixlo_f16 v181, v37, v181, 0
	v_fma_mixlo_f16 v182, v38, v182, 0
	v_fma_mixlo_f16 v183, v39, v183, 0
	v_fma_mixlo_f16 v184, v40, v184, 0
	v_fma_mixlo_f16 v185, v41, v185, 0
	global_store_short v186, v178, s[8:9]
	global_store_short v187, v179, s[8:9]
	global_store_short v188, v180, s[8:9]
	global_store_short v189, v181, s[8:9]
	global_store_short v190, v182, s[8:9]
	global_store_short v191, v183, s[8:9]
	global_store_short v192, v184, s[8:9]
	global_store_short v193, v185, s[8:9]
	v_mul_f32_e32 v178, 0xbfb8aa3b, v58
	v_mul_f32_e32 v179, 0xbfb8aa3b, v59
	v_mul_f32_e32 v180, 0xbfb8aa3b, v60
	v_mul_f32_e32 v181, 0xbfb8aa3b, v61
	v_mul_f32_e32 v182, 0xbfb8aa3b, v62
	v_mul_f32_e32 v183, 0xbfb8aa3b, v63
	v_mul_f32_e32 v184, 0xbfb8aa3b, v64
	v_mul_f32_e32 v185, 0xbfb8aa3b, v65
	v_exp_f32_e32 v178, v178
	v_exp_f32_e32 v179, v179
	v_exp_f32_e32 v180, v180
; DI int TIDX() { int t = threadIdx.x; asm volatile("" : "+v"(t)); return t; }
; DI float sigmoidf_(float x) { return __builtin_amdgcn_rcpf(1.f + __expf(-x)); }
; DI void phase_ffn1(const P& p, int l, int hf, char* smem) {
;     ...
;     const int lane = TIDX() & 63, w = TIDX() >> 6, wm = w >> 1, wn = w & 1, hh = lane >> 5, c = lane & 31;
;     const int ml0 = m0 - mt0 * 128;
; #pragma unroll
;     for (int mi = 0; mi < 4; ++mi) {
;       const int rbase = ml0 + wm * 128 + mi * 32 + 4 * hh, n = c0 + wn * 32 + c;
; #pragma unroll
;       for (int i = 0; i < 16; ++i) {
;         const float g = acc[mi][0][i];
;         act[(size_t)EROW(rbase, i) * 2816 + n] = (h16)(g * sigmoidf_(g) * acc[mi][1][i]);
;       }
;     }
	v_exp_f32_e32 v181, v181
	v_exp_f32_e32 v182, v182
	v_exp_f32_e32 v183, v183
	v_exp_f32_e32 v184, v184
	v_exp_f32_e32 v185, v185
	v_add_u32_e32 v186, 0x6e000, v130
	v_add_u32_e32 v187, 0x6f600, v130
	v_add_u32_e32 v188, 0x70c00, v130
	v_add_u32_e32 v189, 0x72200, v130
	v_add_u32_e32 v190, 0x79000, v130
	v_add_u32_e32 v191, 0x7a600, v130
	v_add_u32_e32 v192, 0x7bc00, v130
	v_add_u32_e32 v193, 0x7d200, v130
	v_add_f32_e32 v178, 1.0, v178
	v_add_f32_e32 v179, 1.0, v179
	v_add_f32_e32 v180, 1.0, v180
	v_add_f32_e32 v181, 1.0, v181
	v_add_f32_e32 v182, 1.0, v182
	v_add_f32_e32 v183, 1.0, v183
	v_add_f32_e32 v184, 1.0, v184
	v_add_f32_e32 v185, 1.0, v185
	v_rcp_f32_e32 v178, v178
	v_rcp_f32_e32 v179, v179
	v_rcp_f32_e32 v180, v180
	v_rcp_f32_e32 v181, v181
	v_rcp_f32_e32 v182, v182
	v_rcp_f32_e32 v183, v183
	v_rcp_f32_e32 v184, v184
	v_rcp_f32_e32 v185, v185
	v_mul_f32_e32 v178, v58, v178
	v_mul_f32_e32 v179, v59, v179
	v_mul_f32_e32 v180, v60, v180
	v_mul_f32_e32 v181, v61, v181
	v_mul_f32_e32 v182, v62, v182
	v_mul_f32_e32 v183, v63, v183
	v_mul_f32_e32 v184, v64, v184
	v_mul_f32_e32 v185, v65, v185
	v_fma_mixlo_f16 v178, v42, v178, 0
	v_fma_mixlo_f16 v179, v43, v179, 0
	v_fma_mixlo_f16 v180, v44, v180, 0
	v_fma_mixlo_f16 v181, v45, v181, 0
	v_fma_mixlo_f16 v182, v46, v182, 0
	v_fma_mixlo_f16 v183, v47, v183, 0
	v_fma_mixlo_f16 v184, v48, v184, 0
	v_fma_mixlo_f16 v185, v49, v185, 0
	global_store_short v186, v178, s[8:9]
	global_store_short v187, v179, s[8:9]
	global_store_short v188, v180, s[8:9]
	global_store_short v189, v181, s[8:9]
	global_store_short v190, v182, s[8:9]
	global_store_short v191, v183, s[8:9]
	global_store_short v192, v184, s[8:9]
	global_store_short v193, v185, s[8:9]
	v_mul_f32_e32 v178, 0xbfb8aa3b, v18
	v_mul_f32_e32 v179, 0xbfb8aa3b, v19
	v_mul_f32_e32 v180, 0xbfb8aa3b, v20
	v_mul_f32_e32 v181, 0xbfb8aa3b, v21
	v_mul_f32_e32 v182, 0xbfb8aa3b, v22
	v_mul_f32_e32 v183, 0xbfb8aa3b, v23
	v_mul_f32_e32 v184, 0xbfb8aa3b, v24
	v_mul_f32_e32 v185, 0xbfb8aa3b, v25
	v_exp_f32_e32 v178, v178
	v_exp_f32_e32 v179, v179
	v_exp_f32_e32 v180, v180
	v_exp_f32_e32 v181, v181
	v_exp_f32_e32 v182, v182
	v_exp_f32_e32 v183, v183
	v_exp_f32_e32 v184, v184
	v_exp_f32_e32 v185, v185
	v_add_u32_e32 v186, 0x84000, v130
	v_add_u32_e32 v187, 0x85600, v130
	v_add_u32_e32 v188, 0x86c00, v130
	v_add_u32_e32 v189, 0x88200, v130
	v_add_u32_e32 v190, 0x8f000, v130
	v_add_u32_e32 v191, 0x90600, v130
	v_add_u32_e32 v192, 0x91c00, v130
	v_add_u32_e32 v193, 0x93200, v130
	v_add_f32_e32 v178, 1.0, v178
	v_add_f32_e32 v179, 1.0, v179
	v_add_f32_e32 v180, 1.0, v180
	v_add_f32_e32 v181, 1.0, v181
	v_add_f32_e32 v182, 1.0, v182
	v_add_f32_e32 v183, 1.0, v183
	v_add_f32_e32 v184, 1.0, v184
	v_add_f32_e32 v185, 1.0, v185
	v_rcp_f32_e32 v178, v178
	v_rcp_f32_e32 v179, v179
	v_rcp_f32_e32 v180, v180
	v_rcp_f32_e32 v181, v181
	v_rcp_f32_e32 v182, v182
	v_rcp_f32_e32 v183, v183
	v_rcp_f32_e32 v184, v184
	v_rcp_f32_e32 v185, v185
	v_mul_f32_e32 v178, v18, v178
	v_mul_f32_e32 v179, v19, v179
	v_mul_f32_e32 v180, v20, v180
	v_mul_f32_e32 v181, v21, v181
	v_mul_f32_e32 v182, v22, v182
	v_mul_f32_e32 v183, v23, v183
	v_mul_f32_e32 v184, v24, v184
	v_mul_f32_e32 v185, v25, v185
	v_fma_mixlo_f16 v178, v2, v178, 0
	v_fma_mixlo_f16 v179, v3, v179, 0
	v_fma_mixlo_f16 v180, v4, v180, 0
	v_fma_mixlo_f16 v181, v5, v181, 0
	v_fma_mixlo_f16 v182, v6, v182, 0
	v_fma_mixlo_f16 v183, v7, v183, 0
	v_fma_mixlo_f16 v184, v8, v184, 0
	v_fma_mixlo_f16 v185, v9, v185, 0
	global_store_short v186, v178, s[8:9]
	global_store_short v187, v179, s[8:9]
	global_store_short v188, v180, s[8:9]
	global_store_short v189, v181, s[8:9]
	global_store_short v190, v182, s[8:9]
	global_store_short v191, v183, s[8:9]
	global_store_short v192, v184, s[8:9]
	global_store_short v193, v185, s[8:9]
	v_mul_f32_e32 v178, 0xbfb8aa3b, v26
	v_mul_f32_e32 v179, 0xbfb8aa3b, v27
	v_mul_f32_e32 v180, 0xbfb8aa3b, v28
	v_mul_f32_e32 v181, 0xbfb8aa3b, v29
	v_mul_f32_e32 v182, 0xbfb8aa3b, v30
	v_mul_f32_e32 v183, 0xbfb8aa3b, v31
	v_mul_f32_e32 v184, 0xbfb8aa3b, v32
	v_mul_f32_e32 v185, 0xbfb8aa3b, v33
	v_exp_f32_e32 v178, v178
	v_exp_f32_e32 v179, v179
	v_exp_f32_e32 v180, v180
	v_exp_f32_e32 v181, v181
	v_exp_f32_e32 v182, v182
	v_exp_f32_e32 v183, v183
	v_exp_f32_e32 v184, v184
	v_exp_f32_e32 v185, v185
	v_add_u32_e32 v186, 0x9a000, v130
	v_add_u32_e32 v187, 0x9b600, v130
	v_add_u32_e32 v188, 0x9cc00, v130
	v_add_u32_e32 v189, 0x9e200, v130
	v_add_u32_e32 v190, 0xa5000, v130
	v_add_u32_e32 v191, 0xa6600, v130
	v_add_u32_e32 v192, 0xa7c00, v130
	v_add_u32_e32 v193, 0xa9200, v130
	v_add_f32_e32 v178, 1.0, v178
	v_add_f32_e32 v179, 1.0, v179
	v_add_f32_e32 v180, 1.0, v180
	v_add_f32_e32 v181, 1.0, v181
	v_add_f32_e32 v182, 1.0, v182
	v_add_f32_e32 v183, 1.0, v183
	v_add_f32_e32 v184, 1.0, v184
	v_add_f32_e32 v185, 1.0, v185
	v_rcp_f32_e32 v178, v178
	v_rcp_f32_e32 v179, v179
	v_rcp_f32_e32 v180, v180
	v_rcp_f32_e32 v181, v181
	v_rcp_f32_e32 v182, v182
	v_rcp_f32_e32 v183, v183
	v_rcp_f32_e32 v184, v184
	v_rcp_f32_e32 v185, v185
	v_mul_f32_e32 v178, v26, v178
	v_mul_f32_e32 v179, v27, v179
	v_mul_f32_e32 v180, v28, v180
	v_mul_f32_e32 v181, v29, v181
	v_mul_f32_e32 v182, v30, v182
	v_mul_f32_e32 v183, v31, v183
	v_mul_f32_e32 v184, v32, v184
	v_mul_f32_e32 v185, v33, v185
	v_fma_mixlo_f16 v178, v10, v178, 0
	v_fma_mixlo_f16 v179, v11, v179, 0
	v_fma_mixlo_f16 v180, v12, v180, 0
	v_fma_mixlo_f16 v181, v13, v181, 0
	v_fma_mixlo_f16 v182, v14, v182, 0
	v_fma_mixlo_f16 v183, v15, v183, 0
	v_fma_mixlo_f16 v184, v16, v184, 0
	v_fma_mixlo_f16 v185, v17, v185, 0
	global_store_short v186, v178, s[8:9]
	global_store_short v187, v179, s[8:9]
	global_store_short v188, v180, s[8:9]
	global_store_short v189, v181, s[8:9]
	global_store_short v190, v182, s[8:9]
	global_store_short v191, v183, s[8:9]
	global_store_short v192, v184, s[8:9]
	global_store_short v193, v185, s[8:9]
